# proj/gate-up unit header: closed-form next tile (pn+4, same row panel) instead of the generic index arithmetic; grid barrier after phase 2 dropped
# speedup vs baseline: 1.0025x; 1.0025x over previous
.LBB0_339:
	s_add_i32 s19, s19, 1
	s_cmp_gt_u32 s19, 1
	s_cselect_b32 s32, 1, 0
	s_cmp_lt_u32 s19, 7
	s_cselect_b64 s[36:37], -1, 0
	s_add_i32 s24, s30, 4
	s_mov_b32 s26, s42

.LBB0_1063:
	s_add_i32 s71, s71, 1
	s_cmp_gt_u32 s71, 1
	s_cselect_b32 s32, 1, 0
	s_cmp_lt_u32 s71, 11
	s_cselect_b64 s[36:37], -1, 0
	s_add_i32 s24, s4, 4
	s_mov_b32 s26, s42
